# v26_stag64
# speedup vs baseline: 1.0093x; 1.0046x over previous
; DI void dsa_item(const Params& p, int b, int blk) {
;     ...
;   constexpr int PSTR = 264;
;   u16* Pb = (u16*)(smem + w * 8192);
;   char* Vc = smem + (w < 4 ? DS_CAND + w * 8192 : DS_MASK + (w - 4) * 8192);
;   const int g16 = lane >> 4, n16 = lane & 15;
;   for (int i = lane; i < PSTR; i += 64) Pb[8 * PSTR + i] = 0;
;   unsigned taddr[8][2];
;   {
;     const unsigned q = n16 >> 2, pp = lane & 3;
;     #pragma unroll
;     for (int c = 0; c < 8; ++c)
;       #pragma unroll
;       for (int t = 0; t < 2; ++t) {
;         const unsigned row = 8 * g16 + 4 * t + q, ch = 2 * c + (pp >> 1);
;         taddr[c][t] = (unsigned)(size_t)(Vc - smem) + 256u * row + 16u * (ch ^ (((row & 3) << 2) | ((row >> 2) & 3))) + 8u * (pp & 1);
;       }
;   }
;   const unsigned lds_base = (unsigned)(size_t)(__attribute__((address_space(3))) char*)smem;
;   const int arow = n16 < 8 ? n16 : 8;
.LBB0_1664:
	s_or_b64 exec, exec, s[4:5]
	v_lshrrev_b32_e32 v7, 4, v187
	v_cmp_gt_i32_e32 vcc, 4, v188
	v_mov_b32_e32 v0, 0x14c00
	v_mov_b32_e32 v2, 0x14000
	v_lshlrev_b32_e32 v156, 3, v7
	v_lshlrev_b32_e32 v12, 1, v7
	v_cndmask_b32_e32 v6, v0, v2, vcc
	v_bfe_u32 v0, v189, 2, 2
	v_and_b32_e32 v9, 12, v189
	v_and_b32_e32 v13, 2, v12
	v_or_b32_e32 v157, 4, v156
	v_bfe_u32 v3, v189, 1, 1
	v_or_b32_e32 v11, v156, v0
	v_or_b32_e32 v14, v13, v9
	v_or_b32_e32 v15, v157, v0
	v_bfe_u32 v0, v157, 2, 2
	v_and_b32_e32 v2, 3, v189
	v_or_b32_e32 v14, v14, v3
	v_bitop3_b32 v17, v0, v3, v9 bitop3:0x36
	v_or_b32_e32 v18, 2, v3
	v_or_b32_e32 v20, 4, v3
	v_or_b32_e32 v22, 6, v3
	v_or_b32_e32 v24, 8, v3
	v_or_b32_e32 v26, 10, v3
	v_or_b32_e32 v28, 12, v3
	v_or_b32_e32 v3, 14, v3
	v_and_b32_e32 v8, 15, v189
	v_bitop3_b32 v19, v13, v18, v9 bitop3:0x36
	v_bitop3_b32 v18, v0, v18, v9 bitop3:0x36
	v_bitop3_b32 v21, v13, v20, v9 bitop3:0x36
	v_bitop3_b32 v20, v0, v20, v9 bitop3:0x36
	v_bitop3_b32 v23, v13, v22, v9 bitop3:0x36
	v_bitop3_b32 v22, v0, v22, v9 bitop3:0x36
	v_bitop3_b32 v25, v13, v24, v9 bitop3:0x36
	v_bitop3_b32 v24, v0, v24, v9 bitop3:0x36
	v_bitop3_b32 v27, v13, v26, v9 bitop3:0x36
	v_bitop3_b32 v26, v0, v26, v9 bitop3:0x36
	v_bitop3_b32 v29, v13, v28, v9 bitop3:0x36
	v_bitop3_b32 v28, v0, v28, v9 bitop3:0x36
	v_bitop3_b32 v30, v13, v3, v9 bitop3:0x36
	v_bitop3_b32 v9, v0, v3, v9 bitop3:0x36
	v_lshlrev_b32_e32 v0, 7, v2
	v_min_u32_e32 v32, 8, v8
	v_lshl_add_u64 v[2:3], s[14:15], 0, v[0:1]
	s_mov_b64 s[4:5], 0xa0cda00
	v_lshlrev_b32_e32 v0, 4, v8
	v_add_u32_e32 v5, 0, v4
	v_lshlrev_b32_e32 v10, 3, v189
	s_waitcnt vmcnt(0)
	v_lshl_add_u64 v[146:147], v[2:3], 0, s[4:5]
	v_lshl_add_u64 v[2:3], s[14:15], 0, v[0:1]
	v_mul_u32_u24_e32 v0, 0x210, v32
	v_and_b32_e32 v32, 48, v187
	v_add3_u32 v161, v5, v0, v32
	v_and_or_b32 v0, v10, 8, 0
	s_mov_b64 s[4:5], 0x15bada00
	v_add3_u32 v0, v6, v4, v0
	v_lshl_add_u64 v[148:149], v[2:3], 0, s[4:5]
	v_lshl_add_u32 v2, v11, 8, v0
	v_lshl_add_u32 v0, v15, 8, v0
	v_lshl_add_u32 v163, v17, 4, v0
	v_lshl_add_u32 v165, v18, 4, v0
	v_lshl_add_u32 v167, v20, 4, v0
	v_lshl_add_u32 v169, v22, 4, v0
	v_lshl_add_u32 v171, v24, 4, v0
	v_lshl_add_u32 v173, v26, 4, v0
	v_lshl_add_u32 v175, v28, 4, v0
	v_lshl_add_u32 v177, v9, 4, v0
	v_lshlrev_b32_e32 v0, 1, v8
	v_lshlrev_b32_e32 v33, 1, v187
	v_lshl_add_u32 v162, v14, 4, v2
	v_lshl_add_u32 v164, v19, 4, v2
	v_lshl_add_u32 v166, v21, 4, v2
	v_lshl_add_u32 v168, v23, 4, v2
	v_lshl_add_u32 v170, v25, 4, v2
	v_lshl_add_u32 v172, v27, 4, v2
	v_lshl_add_u32 v174, v29, 4, v2
	v_lshl_add_u32 v176, v30, 4, v2
	v_lshl_add_u64 v[2:3], s[14:15], 0, v[0:1]
	v_bitop3_b32 v0, v12, v8, 2 bitop3:0x6c
	v_add_u32_e32 v31, v5, v6
	v_add_u32_e32 v160, v5, v33
	v_lshlrev_b32_e32 v5, 4, v0
	v_bitop3_b32 v0, v12, v8, 4 bitop3:0x36
	v_lshlrev_b32_e32 v9, 4, v0
	v_bitop3_b32 v0, v13, v8, 8 bitop3:0x36
	v_lshrrev_b32_e32 v16, 2, v157
	v_lshlrev_b32_e32 v11, 4, v0
	v_bitop3_b32 v0, v12, v8, 12 bitop3:0x36
	v_or_b32_e32 v195, 5, v156
	v_lshlrev_b32_e32 v12, 4, v0
	v_bitop3_b32 v0, v16, v8, 3 bitop3:0x6c
	v_lshlrev_b32_e32 v15, 4, v0
	v_lshrrev_b32_e32 v0, 2, v195
	v_or_b32_e32 v196, 6, v156
	v_bitop3_b32 v0, v0, v8, 4 bitop3:0x36
	v_lshlrev_b32_e32 v17, 4, v0
	v_bfe_u32 v0, v196, 2, 2
	v_or_b32_e32 v197, 7, v156
	v_bitop3_b32 v0, v0, v8, 8 bitop3:0x36
	v_lshlrev_b32_e32 v19, 4, v0
	v_lshrrev_b32_e32 v0, 2, v197
	v_bitop3_b32 v0, v0, v8, 12 bitop3:0x36
	v_lshlrev_b32_e32 v8, 4, v0
	v_lshlrev_b32_e32 v0, 9, v7
	v_or_b32_e32 v192, 1, v156
	v_or_b32_e32 v193, 2, v156
	v_or_b32_e32 v194, 3, v156
	v_lshl_add_u64 v[2:3], v[2:3], 0, v[0:1]
	s_mov_b64 s[4:5], 0x18349a00
	s_add_u32 s0, s14, 0x1538da00
	v_lshl_add_u32 v4, v7, 11, v31
	v_lshl_add_u32 v6, v192, 8, v31
	v_lshl_add_u32 v10, v193, 8, v31
	v_lshl_add_u32 v13, v194, 8, v31
	v_lshl_add_u32 v14, v157, 8, v31
	v_lshl_add_u32 v16, v195, 8, v31
	v_lshl_add_u32 v18, v196, 8, v31
	v_lshl_add_u32 v20, v197, 8, v31
	v_lshl_add_u64 v[150:151], v[2:3], 0, s[4:5]
	v_lshl_or_b32 v0, v188, 11, v32
	v_readlane_b32 s4, v255, 7
	s_addc_u32 s1, s15, 0
	v_lshlrev_b32_e32 v158, 2, v188
	v_add_u32_e32 v159, s3, v33
	v_cmp_gt_u32_e64 s[6:7], 32, v187
	v_cmp_gt_u32_e64 s[8:9], 16, v187
	v_or_b32_e32 v189, 64, v187
	v_or_b32_e32 v190, 0x80, v187
	v_or_b32_e32 v191, 0xc0, v187
	v_add_u32_e32 v188, s4, v0
	s_mov_b32 s24, 0
	v_add_u32_e32 v198, v4, v5
	v_add_u32_e32 v199, v6, v9
	v_add_u32_e32 v200, v10, v11
	v_add_u32_e32 v201, v13, v12
	v_add_u32_e32 v202, v14, v15
	v_add_u32_e32 v203, v16, v17
	v_add_u32_e32 v204, v18, v19
	v_add_u32_e32 v205, v20, v8
	v_readfirstlane_b32 s100, v178
	s_nop 3
	s_lshr_b32 s100, s100, 6
.Lsa_stag:
	s_cmp_eq_u32 s100, 0
	s_cbranch_scc1 .Lsa_stag_done
	s_sleep 64
	s_sub_u32 s100, s100, 1
	s_branch .Lsa_stag
.Lsa_stag_done:
	s_branch .LBB0_1667
.LBB0_1665:
	s_or_b64 exec, exec, s[10:11]
	s_waitcnt lgkmcnt(0)
